# v44 + MLA half 2 QK: K-fragment reads software-pipelined one MFMA pair ahead (alternate buffer v[206:213]), lgkmcnt(2) waits
# baseline (speedup 1.0000x reference)
.LBB0_549:
	v_cndmask_b32_e64 v165, v165, v202, s[4:5]
	v_mul_f32_e32 v154, 0xbdd53b94, v165
	v_fmamk_f32 v202, v69, 0x3dd53b94, v154
	v_fmamk_f32 v215, v70, 0x3dd53b94, v154
	v_fmamk_f32 v155, v66, 0x3dd53b94, v154
	v_fmamk_f32 v156, v67, 0x3dd53b94, v154
	v_fmamk_f32 v157, v68, 0x3dd53b94, v154
	v_fmamk_f32 v216, v71, 0x3dd53b94, v154
	v_fmamk_f32 v217, v72, 0x3dd53b94, v154
	v_fmamk_f32 v218, v73, 0x3dd53b94, v154
	ds_read_b128 v[66:69], v174 offset:32768
	ds_read_b128 v[70:73], v174 offset:40960
	ds_read_b128 v[146:149], v176 offset:32768
	ds_read_b128 v[150:153], v176 offset:40960
	ds_read_b128 v[206:209], v178 offset:32768
	ds_read_b128 v[210:213], v178 offset:40960
	v_fmamk_f32 v224, v82, 0x3dd53b94, v154
	v_fmamk_f32 v225, v83, 0x3dd53b94, v154
	v_fmamk_f32 v226, v84, 0x3dd53b94, v154
	v_fmamk_f32 v227, v85, 0x3dd53b94, v154
	v_fmamk_f32 v228, v86, 0x3dd53b94, v154
	v_fmamk_f32 v229, v87, 0x3dd53b94, v154
	v_fmamk_f32 v230, v88, 0x3dd53b94, v154
	v_fmamk_f32 v231, v89, 0x3dd53b94, v154
	v_fmamk_f32 v234, v90, 0x3dd53b94, v154
	v_fmamk_f32 v235, v91, 0x3dd53b94, v154
	v_fmamk_f32 v236, v92, 0x3dd53b94, v154
	v_fmamk_f32 v237, v93, 0x3dd53b94, v154
	v_fmamk_f32 v238, v94, 0x3dd53b94, v154
	v_fmamk_f32 v239, v95, 0x3dd53b94, v154
	v_fmamk_f32 v240, v96, 0x3dd53b94, v154
	v_fmamk_f32 v241, v97, 0x3dd53b94, v154
	s_waitcnt lgkmcnt(4)
	v_mfma_f32_32x32x16_bf16 v[82:97], v[66:69], v[142:145], 0
	v_fmamk_f32 v232, v79, 0x3dd53b94, v154
	v_fmamk_f32 v233, v80, 0x3dd53b94, v154
	v_fmamk_f32 v219, v74, 0x3dd53b94, v154
	v_fmamk_f32 v220, v75, 0x3dd53b94, v154
	v_fmamk_f32 v221, v76, 0x3dd53b94, v154
	v_fmamk_f32 v222, v77, 0x3dd53b94, v154
	v_fmamk_f32 v223, v78, 0x3dd53b94, v154
	v_fmac_f32_e32 v154, 0x3dd53b94, v81
	v_mfma_f32_32x32x16_bf16 v[66:81], v[70:73], v[142:145], 0
	v_exp_f32_e32 v224, v224
	v_exp_f32_e32 v225, v225
	v_exp_f32_e32 v226, v226
	v_add_f32_e32 v245, 0, v224
	v_add_f32_e32 v245, v225, v245
	v_add_f32_e32 v245, v226, v245
	s_waitcnt lgkmcnt(2)
	v_mfma_f32_32x32x16_bf16 v[82:97], v[146:149], v[138:141], v[82:97]
	v_exp_f32_e32 v227, v227
	v_exp_f32_e32 v228, v228
	v_add_f32_e32 v245, v227, v245
	v_add_f32_e32 v245, v228, v245
	v_mfma_f32_32x32x16_bf16 v[66:81], v[150:153], v[138:141], v[66:81]
	ds_read_b128 v[146:149], v180 offset:32768
	ds_read_b128 v[150:153], v180 offset:40960
	v_exp_f32_e32 v229, v229
	v_exp_f32_e32 v230, v230
	v_add_f32_e32 v245, v229, v245
	v_add_f32_e32 v245, v230, v245
	s_cmp_lg_u32 s98, 0
	s_cbranch_scc1 .Lattn_mla_nopf
	s_add_u32 s0, s38, s20
	s_addc_u32 s1, s39, s21
	s_add_u32 s100, s0, s42
	s_addc_u32 s101, s1, s43
	s_mov_b32 m0, s93
	v_lshl_add_u64 v[254:255], v[246:247], 0, s[100:101]
	global_load_lds_dwordx4 v[254:255], off
	s_add_u32 s100, s0, s46
	s_addc_u32 s101, s1, s47
	s_mov_b32 m0, s94
	v_lshl_add_u64 v[254:255], v[246:247], 0, s[100:101]
	global_load_lds_dwordx4 v[254:255], off
	s_add_u32 s100, s0, s44
	s_addc_u32 s101, s1, s45
	s_add_i32 s98, s89, s24
	s_mov_b32 m0, s98
	v_lshl_add_u64 v[254:255], v[248:249], 0, s[100:101]
	global_load_lds_dwordx4 v[254:255], off
	s_add_u32 s100, s0, s50
	s_addc_u32 s101, s1, s51
	s_add_i32 m0, s98, 0x2000
	v_lshl_add_u64 v[254:255], v[248:249], 0, s[100:101]
	global_load_lds_dwordx4 v[254:255], off
	s_add_u32 s0, s38, s88
	s_addc_u32 s1, s39, s87
	s_add_u32 s0, s0, s58
	s_addc_u32 s1, s1, s59
	s_mov_b32 m0, s95
	v_lshl_add_u64 v[254:255], v[250:251], 0, s[0:1]
	global_load_lds_dwordx4 v[254:255], off
.Lattn_mla_nopf:
	s_waitcnt lgkmcnt(2)
	v_mfma_f32_32x32x16_bf16 v[82:97], v[206:209], v[134:137], v[82:97]
	v_mfma_f32_32x32x16_bf16 v[66:81], v[210:213], v[134:137], v[66:81]
	ds_read_b128 v[206:209], v182 offset:32768
	ds_read_b128 v[210:213], v182 offset:40960
	v_exp_f32_e32 v231, v231
	v_exp_f32_e32 v234, v234
	v_exp_f32_e32 v235, v235
	v_add_f32_e32 v245, v231, v245
	v_add_f32_e32 v245, v234, v245
	v_add_f32_e32 v245, v235, v245
	s_waitcnt lgkmcnt(2)
	v_mfma_f32_32x32x16_bf16 v[82:97], v[146:149], v[130:133], v[82:97]
	v_mfma_f32_32x32x16_bf16 v[66:81], v[150:153], v[130:133], v[66:81]
	ds_read_b128 v[146:149], v186 offset:32768
	ds_read_b128 v[150:153], v186 offset:40960
	v_exp_f32_e32 v236, v236
	v_exp_f32_e32 v237, v237
	v_exp_f32_e32 v238, v238
	v_add_f32_e32 v245, v236, v245
	v_add_f32_e32 v245, v237, v245
	v_add_f32_e32 v245, v238, v245
	s_waitcnt lgkmcnt(2)
	v_mfma_f32_32x32x16_bf16 v[82:97], v[206:209], v[126:129], v[82:97]
	v_mfma_f32_32x32x16_bf16 v[66:81], v[210:213], v[126:129], v[66:81]
	ds_read_b128 v[206:209], v188 offset:32768
	ds_read_b128 v[210:213], v188 offset:40960
	v_exp_f32_e32 v239, v239
	v_exp_f32_e32 v240, v240
	v_exp_f32_e32 v241, v241
	v_add_f32_e32 v245, v239, v245
	v_add_f32_e32 v245, v240, v245
	v_add_f32_e32 v245, v241, v245
	s_waitcnt lgkmcnt(2)
	v_mfma_f32_32x32x16_bf16 v[82:97], v[146:149], v[122:125], v[82:97]
	v_mfma_f32_32x32x16_bf16 v[66:81], v[150:153], v[122:125], v[66:81]
	ds_read_b128 v[146:149], v190 offset:32768
	ds_read_b128 v[150:153], v190 offset:40960
	v_exp_f32_e32 v155, v155
	v_exp_f32_e32 v156, v156
	v_exp_f32_e32 v157, v157
	v_add_f32_e32 v245, v155, v245
	v_add_f32_e32 v245, v156, v245
	v_add_f32_e32 v245, v157, v245
	s_waitcnt lgkmcnt(2)
	v_mfma_f32_32x32x16_bf16 v[82:97], v[206:209], v[118:121], v[82:97]
	v_mfma_f32_32x32x16_bf16 v[66:81], v[210:213], v[118:121], v[66:81]
	ds_read_b128 v[206:209], v192
	ds_read_b128 v[210:213], v192 offset:4096
	v_exp_f32_e32 v202, v202
	v_exp_f32_e32 v215, v215
	v_exp_f32_e32 v216, v216
	v_add_f32_e32 v245, v202, v245
	v_add_f32_e32 v245, v215, v245
	v_add_f32_e32 v245, v216, v245
	s_waitcnt lgkmcnt(2)
	v_mfma_f32_32x32x16_bf16 v[82:97], v[146:149], v[114:117], v[82:97]
	v_mfma_f32_32x32x16_bf16 v[66:81], v[150:153], v[114:117], v[66:81]
	ds_read_b128 v[146:149], v194
	ds_read_b128 v[150:153], v194 offset:4096
	v_exp_f32_e32 v217, v217
	v_exp_f32_e32 v218, v218
	v_exp_f32_e32 v219, v219
	v_add_f32_e32 v245, v217, v245
	v_add_f32_e32 v245, v218, v245
	v_add_f32_e32 v245, v219, v245
	s_waitcnt lgkmcnt(2)
	v_mfma_f32_32x32x16_bf16 v[82:97], v[206:209], v[110:113], v[82:97]
	v_mfma_f32_32x32x16_bf16 v[66:81], v[210:213], v[110:113], v[66:81]
	ds_read_b128 v[206:209], v196
	ds_read_b128 v[210:213], v196 offset:4096
	v_exp_f32_e32 v220, v220
	v_exp_f32_e32 v221, v221
	v_exp_f32_e32 v222, v222
	v_add_f32_e32 v245, v220, v245
	v_add_f32_e32 v245, v221, v245
	v_add_f32_e32 v245, v222, v245
	s_waitcnt lgkmcnt(2)
	v_mfma_f32_32x32x16_bf16 v[82:97], v[146:149], v[106:109], v[82:97]
	v_mfma_f32_32x32x16_bf16 v[66:81], v[150:153], v[106:109], v[66:81]
	ds_read_b128 v[146:149], v199
	ds_read_b128 v[150:153], v199 offset:4096
	v_exp_f32_e32 v223, v223
	v_exp_f32_e32 v242, v232
	v_exp_f32_e32 v243, v233
	v_add_f32_e32 v245, v223, v245
	v_add_f32_e32 v245, v242, v245
	v_add_f32_e32 v245, v243, v245
	s_waitcnt lgkmcnt(2)
	v_mfma_f32_32x32x16_bf16 v[82:97], v[206:209], v[102:105], v[82:97]
	v_mfma_f32_32x32x16_bf16 v[66:81], v[210:213], v[102:105], v[66:81]
	v_exp_f32_e32 v244, v154
	s_waitcnt lgkmcnt(0)
	v_mfma_f32_32x32x16_bf16 v[82:97], v[146:149], v[98:101], v[82:97]
	v_mfma_f32_32x32x16_bf16 v[66:81], v[150:153], v[98:101], v[66:81]
	v_add_f32_e32 v232, v244, v245
	v_mov_b32_e32 v233, v232
	s_nop 1
	v_permlane32_swap_b32_e32 v232, v233
	v_cvt_pk_bf16_f32 v146, v224, v225
	v_cvt_pk_bf16_f32 v147, v226, v227
	v_cvt_pk_bf16_f32 v148, v228, v229
	v_cvt_pk_bf16_f32 v149, v230, v231
	v_cvt_pk_bf16_f32 v150, v234, v235
	v_cvt_pk_bf16_f32 v151, v236, v237
	v_cvt_pk_bf16_f32 v152, v238, v239
	v_cvt_pk_bf16_f32 v153, v240, v241
	v_cvt_pk_bf16_f32 v154, v155, v156
	v_cvt_pk_bf16_f32 v155, v157, v202
	v_cvt_pk_bf16_f32 v156, v215, v216
	v_cvt_pk_bf16_f32 v157, v217, v218
	v_cvt_pk_bf16_f32 v216, v219, v220
	v_cvt_pk_bf16_f32 v217, v221, v222
	v_cvt_pk_bf16_f32 v218, v223, v242
	v_cvt_pk_bf16_f32 v219, v243, v244
	s_nop 0
	v_permlane32_swap_b32_e32 v146, v148
	v_permlane32_swap_b32_e32 v147, v149
	v_permlane32_swap_b32_e32 v150, v152
	v_permlane32_swap_b32_e32 v151, v153
	v_permlane32_swap_b32_e32 v154, v156
	v_permlane32_swap_b32_e32 v155, v157
	v_permlane32_swap_b32_e32 v216, v218
	v_permlane32_swap_b32_e32 v217, v219
	v_lshl_add_u32 v242, s23, 14, v200
	ds_read_b64_tr_b16 v[220:221], v242 offset:0
	ds_read_b64_tr_b16 v[222:223], v242 offset:0x800
	ds_read_b64_tr_b16 v[224:225], v242 offset:0x1000
	ds_read_b64_tr_b16 v[226:227], v242 offset:0x1800
	ds_read_b64_tr_b16 v[228:229], v242 offset:0x2000
	ds_read_b64_tr_b16 v[230:231], v242 offset:0x2800
	ds_read_b64_tr_b16 v[234:235], v242 offset:0x3000
	ds_read_b64_tr_b16 v[236:237], v242 offset:0x3800
	s_nop 0
	s_waitcnt lgkmcnt(6)
	v_mfma_f32_32x32x16_bf16 v[2:17], v[146:149], v[220:223], v[2:17]
	ds_read_b64_tr_b16 v[220:221], v242 offset:0x200
	ds_read_b64_tr_b16 v[222:223], v242 offset:0xa00
	v_max_f32_e32 v202, v83, v83
	v_max_f32_e32 v215, v82, v82
	v_max_f32_e32 v202, v215, v202
	v_max3_f32 v202, v202, v84, v85
	v_max3_f32 v202, v202, v86, v87
	s_waitcnt lgkmcnt(6)
	v_mfma_f32_32x32x16_bf16 v[2:17], v[150:153], v[224:227], v[2:17]
	ds_read_b64_tr_b16 v[224:225], v242 offset:0x1200
	ds_read_b64_tr_b16 v[226:227], v242 offset:0x1a00
	v_max3_f32 v202, v202, v88, v89
	v_max3_f32 v202, v202, v90, v91
	v_max3_f32 v202, v202, v92, v93
	v_max3_f32 v202, v202, v94, v95
	v_max3_f32 v202, v202, v96, v97
	s_waitcnt lgkmcnt(6)
	v_mfma_f32_32x32x16_bf16 v[2:17], v[154:157], v[228:231], v[2:17]
	ds_read_b64_tr_b16 v[228:229], v242 offset:0x2200
	ds_read_b64_tr_b16 v[230:231], v242 offset:0x2a00
	ds_read_b64_tr_b16 v[238:239], v242 offset:0x3200
	ds_read_b64_tr_b16 v[240:241], v242 offset:0x3a00
	s_waitcnt lgkmcnt(8)
	v_mfma_f32_32x32x16_bf16 v[2:17], v[216:219], v[234:237], v[2:17]
	s_waitcnt lgkmcnt(6)
	v_mfma_f32_32x32x16_bf16 v[50:65], v[146:149], v[220:223], v[50:65]
	v_max3_f32 v202, v202, v66, v67
	v_max3_f32 v202, v202, v68, v69
	v_max3_f32 v202, v202, v70, v71
	v_max3_f32 v202, v202, v72, v73
	v_max3_f32 v202, v202, v74, v75
	v_max3_f32 v202, v202, v76, v77
	v_max3_f32 v202, v202, v78, v79
	s_waitcnt lgkmcnt(4)
	v_mfma_f32_32x32x16_bf16 v[50:65], v[150:153], v[224:227], v[50:65]
	v_max3_f32 v202, v202, v80, v81
	v_mov_b32_e32 v215, v202
	s_nop 1
	v_permlane32_swap_b32_e32 v202, v215
	v_max_f32_e32 v215, v215, v215
	v_max_f32_e32 v202, v202, v202
	v_max_f32_e32 v202, v202, v215
	v_max_f32_e32 v220, v165, v165
	v_sub_f32_e32 v215, v202, v165
	v_max_f32_e32 v202, v220, v202
	v_sub_f32_e32 v220, v165, v202
	v_mul_f32_e32 v220, 0x3dd53b94, v220
	s_waitcnt lgkmcnt(2)
	v_mfma_f32_32x32x16_bf16 v[50:65], v[154:157], v[228:231], v[50:65]
	v_exp_f32_e32 v220, v220
	v_cmp_ge_f32_e32 vcc, s77, v215
	s_cmp_eq_u64 vcc, exec
	s_cselect_b64 s[4:5], -1, 0
	v_cndmask_b32_e64 v215, v220, 1.0, s[4:5]
	ds_read_b64_tr_b16 v[220:221], v242 offset:0x400
	ds_read_b64_tr_b16 v[222:223], v242 offset:0xc00
	ds_read_b64_tr_b16 v[224:225], v242 offset:0x1400
	s_waitcnt lgkmcnt(3)
	v_mfma_f32_32x32x16_bf16 v[50:65], v[216:219], v[238:241], v[50:65]
	ds_read_b64_tr_b16 v[226:227], v242 offset:0x1c00
	ds_read_b64_tr_b16 v[228:229], v242 offset:0x2400
	ds_read_b64_tr_b16 v[230:231], v242 offset:0x2c00
	ds_read_b64_tr_b16 v[234:235], v242 offset:0x3400
	ds_read_b64_tr_b16 v[236:237], v242 offset:0x3c00
	s_waitcnt lgkmcnt(6)
	v_mfma_f32_32x32x16_bf16 v[34:49], v[146:149], v[220:223], v[34:49]
	ds_read_b64_tr_b16 v[220:221], v242 offset:0x600
	ds_read_b64_tr_b16 v[222:223], v242 offset:0xe00
	s_waitcnt lgkmcnt(6)
	v_mfma_f32_32x32x16_bf16 v[34:49], v[150:153], v[224:227], v[34:49]
	ds_read_b64_tr_b16 v[224:225], v242 offset:0x1600
	ds_read_b64_tr_b16 v[226:227], v242 offset:0x1e00
	s_waitcnt lgkmcnt(6)
	v_mfma_f32_32x32x16_bf16 v[34:49], v[154:157], v[228:231], v[34:49]
	ds_read_b64_tr_b16 v[228:229], v242 offset:0x2600
	ds_read_b64_tr_b16 v[230:231], v242 offset:0x2e00
	ds_read_b64_tr_b16 v[238:239], v242 offset:0x3600
	ds_read_b64_tr_b16 v[240:241], v242 offset:0x3e00
	s_waitcnt lgkmcnt(8)
	v_mfma_f32_32x32x16_bf16 v[34:49], v[216:219], v[234:237], v[34:49]
	s_waitcnt lgkmcnt(6)
	v_mfma_f32_32x32x16_bf16 v[18:33], v[146:149], v[220:223], v[18:33]
	v_cmp_gt_f32_e32 vcc, 1.0, v215
	s_waitcnt lgkmcnt(4)
	v_mfma_f32_32x32x16_bf16 v[18:33], v[150:153], v[224:227], v[18:33]
	s_waitcnt lgkmcnt(2)
	v_mfma_f32_32x32x16_bf16 v[18:33], v[154:157], v[228:231], v[18:33]
	s_waitcnt lgkmcnt(0)
	v_mfma_f32_32x32x16_bf16 v[18:33], v[216:219], v[238:241], v[18:33]
	s_cbranch_vccz .LBB0_553
	s_and_saveexec_b64 s[0:1], s[2:3]
	ds_write_b32 v170, v215 offset:128
	s_or_b64 exec, exec, s[0:1]
	s_waitcnt lgkmcnt(0)
	ds_read_b128 v[146:149], v158 offset:224
	ds_read_b128 v[150:153], v158 offset:192
	ds_read_b128 v[154:157], v158 offset:160
	ds_read_b128 v[216:219], v158 offset:128
	s_waitcnt lgkmcnt(0)
	v_pk_mul_f32 v[16:17], v[16:17], v[148:149]
	v_pk_mul_f32 v[12:13], v[12:13], v[152:153]
	v_pk_mul_f32 v[8:9], v[8:9], v[156:157]
	v_pk_mul_f32 v[4:5], v[4:5], v[218:219]
	v_pk_mul_f32 v[14:15], v[14:15], v[146:147]
	v_pk_mul_f32 v[10:11], v[10:11], v[150:151]
	v_pk_mul_f32 v[6:7], v[6:7], v[154:155]
	v_pk_mul_f32 v[2:3], v[2:3], v[216:217]
	v_pk_mul_f32 v[64:65], v[64:65], v[148:149]
	v_pk_mul_f32 v[60:61], v[60:61], v[152:153]
	v_pk_mul_f32 v[56:57], v[56:57], v[156:157]
	v_pk_mul_f32 v[52:53], v[52:53], v[218:219]
	v_pk_mul_f32 v[62:63], v[62:63], v[146:147]
	v_pk_mul_f32 v[58:59], v[58:59], v[150:151]
	v_pk_mul_f32 v[54:55], v[54:55], v[154:155]
	v_pk_mul_f32 v[50:51], v[50:51], v[216:217]
	v_pk_mul_f32 v[48:49], v[48:49], v[148:149]
	v_pk_mul_f32 v[44:45], v[44:45], v[152:153]
	v_pk_mul_f32 v[40:41], v[40:41], v[156:157]
	v_pk_mul_f32 v[36:37], v[36:37], v[218:219]
	v_pk_mul_f32 v[46:47], v[46:47], v[146:147]
	v_pk_mul_f32 v[42:43], v[42:43], v[150:151]
	v_pk_mul_f32 v[38:39], v[38:39], v[154:155]
	v_pk_mul_f32 v[34:35], v[34:35], v[216:217]
	v_pk_mul_f32 v[32:33], v[32:33], v[148:149]
	v_pk_mul_f32 v[28:29], v[28:29], v[152:153]
	v_pk_mul_f32 v[24:25], v[24:25], v[156:157]
	v_pk_mul_f32 v[20:21], v[20:21], v[218:219]
	v_pk_mul_f32 v[30:31], v[30:31], v[146:147]
	v_pk_mul_f32 v[26:27], v[26:27], v[150:151]
	v_pk_mul_f32 v[22:23], v[22:23], v[154:155]
	v_pk_mul_f32 v[18:19], v[18:19], v[216:217]
